# c24 with the MLA deferred-max threshold raised from 8 to 24 log2 units (P <= 2^24, exact rescaling identity; fewer rescale events)
# speedup vs baseline: 1.0147x; 1.0147x over previous
.LBB0_856:
	s_cmp_lt_i32 s62, 6
	s_cselect_b64 s[0:1], -1, 0
	s_and_b64 s[6:7], s[0:1], s[4:5]
	s_andn2_b64 vcc, exec, s[6:7]
	s_cbranch_vccnz .LBB0_897
	v_mbcnt_hi_u32_b32 v0, -1, v228
	v_readlane_b32 s0, v244, 2
	s_mov_b32 s9, 0
	v_mov_b32_e32 v229, v0
	s_mov_b64 s[4:5], s[24:25]
	s_cmpk_gt_i32 s0, 0xff
	s_cbranch_scc1 .LBB0_897
	s_load_dwordx2 s[4:5], s[4:5], 0xa8
	s_mov_b32 s34, 0xfffe0000
	s_mov_b64 s[10:11], 0x80000
	s_movk_i32 s27, 0xc00
	v_mov_b32_e32 v1, 0
	s_waitcnt lgkmcnt(0)
	s_add_u32 s0, s4, 0x3200000
	s_addc_u32 s1, s5, 0
	s_add_u32 s2, s4, 0x7200000
	s_addc_u32 s3, s5, 0
	s_add_u32 s20, s4, 0xa600000
	s_addc_u32 s21, s5, 0
	s_add_u32 s22, s4, 0xa800000
	s_addc_u32 s23, s5, 0
	s_and_b32 s8, s91, 0xffffffc0
	s_lshl_b32 s24, s90, 5
	s_add_u32 s25, s4, 0x32a0100
	v_add_u32_e32 v230, s8, v0
	s_addc_u32 s26, s5, 0
	s_movk_i32 s28, 0xf840
	s_mov_b64 s[12:13], 0x80
	s_mov_b64 s[14:15], 0x100
	s_mov_b64 s[16:17], 0x20100
	s_mov_b64 s[18:19], 0x20000
	s_mov_b32 s29, 0x41c00000
	s_mov_b32 s35, -1
	s_movk_i32 s30, 0x7fff
	v_mov_b32_e32 v231, 0xf149f2ca
	v_readlane_b32 s31, v244, 2
	s_branch .LBB0_860
